# plus assemble hyena-output transposition: counted waits keep the next tile's words in flight
# baseline (speedup 1.0000x reference)
; #define LAS __attribute__((address_space(3)))
; __device__ __forceinline__ unsigned pk2(float lo, float hi) { unsigned r; asm("v_cvt_pk_bf16_f32 %0, %1, %2" : "=v"(r) : "v"(lo), "v"(hi)); return r; }
; __device__ __forceinline__ float bflo(unsigned u) { return __uint_as_float(u << 16); }
; __device__ __forceinline__ float bfhi(unsigned u) { return __uint_as_float(u & 0xffff0000u); }
; __device__ __forceinline__ void assemble_phase(const Params& P, int l, LAS unsigned char* lds) {
;     ...
;             { const int tt = tid & 63;
; #pragma unroll
;               for (int u = 0; u < 8; ++u) { const int cc = (tid >> 6) + 8 * u; const unsigned v = crv[u];
;                 L[(0 * 64 + tt) * 65 + cc] = bflo(v); L[(1 * 64 + tt) * 65 + cc] = bfhi(v); } }
;             asm volatile("s_waitcnt lgkmcnt(0)" ::: "memory"); __builtin_amdgcn_s_barrier(); asm volatile("" ::: "memory");
; #pragma unroll
;             for (int u = 0; u < 2; ++u) { const int task = tid + 512 * u, rowi = task >> 3, bb = rowi >> 6, tt = rowi & 63, ch8 = task & 7;
;                 const LAS float* lp = L + (bb * 64 + tt) * 65 + ch8 * 8;
;                 u32x4 o; o.x = pk2(lp[0], lp[1]); o.y = pk2(lp[2], lp[3]); o.z = pk2(lp[4], lp[5]); o.w = pk2(lp[6], lp[7]);
;                 *(u32x4*)(BR + ((size_t)bb * TPB + CTX + ti * 64 + tt) * 3072 + ct * 64 + ch8 * 8) = o; }
;             asm volatile("s_waitcnt lgkmcnt(0)" ::: "memory"); __builtin_amdgcn_s_barrier(); asm volatile("" ::: "memory");
; #pragma unroll
;             for (int u = 0; u < 8; ++u) crv[u] = nrv[u];
.Lasm_tr_join:
	s_and_b32 s6, s12, 0xffffffc0
	s_waitcnt lgkmcnt(0)
	s_barrier
	s_ashr_i32 s7, s6, 31
	v_lshl_add_u64 v[34:35], s[6:7], 0, v[2:3]
	s_and_b32 s6, s11, 0x3c0
	ds_read2_b32 v[16:17], v14 offset1:1
	ds_read2_b32 v[18:19], v14 offset0:2 offset1:3
	ds_read2_b32 v[38:39], v14 offset0:6 offset1:7
	s_lshl_b32 s86, s6, 1
	s_waitcnt lgkmcnt(2)
	v_cvt_pk_bf16_f32 v16, v16, v17
	s_waitcnt lgkmcnt(1)
	v_cvt_pk_bf16_f32 v17, v18, v19
	ds_read2_b32 v[18:19], v14 offset0:4 offset1:5
	v_lshl_add_u64 v[36:37], v[4:5], 0, s[86:87]
	s_waitcnt lgkmcnt(0)
	v_cvt_pk_bf16_f32 v18, v18, v19
	v_cvt_pk_bf16_f32 v19, v38, v39
	v_lshl_add_u64 v[38:39], v[34:35], 0, v[6:7]
	v_mad_u64_u32 v[40:41], s[6:7], v38, s37, v[36:37]
	v_mov_b32_e32 v24, v41
	v_lshl_add_u64 v[34:35], v[34:35], 0, v[8:9]
	v_mad_u64_u32 v[38:39], s[6:7], v39, s37, v[24:25]
	v_mad_u64_u32 v[36:37], s[6:7], v34, s37, v[36:37]
	v_mov_b32_e32 v41, v38
	v_mov_b32_e32 v24, v37
	global_store_dwordx4 v[40:41], v[16:19], off
	ds_read2_b32 v[16:17], v15 offset1:1
	ds_read2_b32 v[18:19], v15 offset0:2 offset1:3
	ds_read2_b32 v[38:39], v15 offset0:6 offset1:7
	v_mad_u64_u32 v[34:35], s[6:7], v35, s37, v[24:25]
	s_waitcnt lgkmcnt(2)
	v_cvt_pk_bf16_f32 v16, v16, v17
	s_waitcnt lgkmcnt(1)
	v_cvt_pk_bf16_f32 v17, v18, v19
	ds_read2_b32 v[18:19], v15 offset0:4 offset1:5
	v_mov_b32_e32 v37, v34
	s_waitcnt lgkmcnt(0)
	v_cvt_pk_bf16_f32 v18, v18, v19
	v_cvt_pk_bf16_f32 v19, v38, v39
	global_store_dwordx4 v[36:37], v[16:19], off
	s_waitcnt lgkmcnt(0)
	s_barrier
	s_and_b64 vcc, exec, s[4:5]
	s_mov_b32 s12, s10
	s_mov_b32 s11, s9
	s_waitcnt vmcnt(0)
	v_mov_b32_e32 v16, v22
	v_mov_b32_e32 v17, v25
	v_mov_b32_e32 v18, v26
	v_mov_b32_e32 v19, v27
	v_mov_b32_e32 v21, v29
	v_mov_b32_e32 v23, v30
	v_mov_b32_e32 v24, v31
	v_mov_b32_e32 v28, v32
	s_cbranch_vccnz .LBB0_813

; __device__ __forceinline__ float bflo(unsigned u) { return __uint_as_float(u << 16); }
; __device__ __forceinline__ float bfhi(unsigned u) { return __uint_as_float(u & 0xffff0000u); }
; #define ASY_LOAD(rv_, item_) do { const int ti_ = (item_) >> 4, ct_ = (item_) & 15, tt_ = tid & 63; \
;             _Pragma("unroll") for (int u = 0; u < 8; ++u) { const int cc = (tid >> 6) + 8 * u; rv_[u] = ZT[(size_t)(ct_ * 64 + cc) * 4096 + ti_ * 64 + tt_]; } } while (0)
; __device__ __forceinline__ void assemble_phase(const Params& P, int l, LAS unsigned char* lds) {
;     ...
;         unsigned crv[8];
; #pragma unroll
;         for (int u = 0; u < 8; ++u) crv[u] = 0u;
;         if ((int)blockIdx.x < 64 * 16) ASY_LOAD(crv, blockIdx.x);
; #pragma unroll 1
;         for (int item = blockIdx.x; item < 64 * 16; item += G) {
;             const int ti = item >> 4, ct = item & 15;
;             unsigned nrv[8];
; #pragma unroll
;             for (int u = 0; u < 8; ++u) nrv[u] = 0u;
;             if (item + G < 64 * 16) ASY_LOAD(nrv, item + G);
;             { const int tt = tid & 63;
; #pragma unroll
;               for (int u = 0; u < 8; ++u) { const int cc = (tid >> 6) + 8 * u; const unsigned v = crv[u];
;                 L[(0 * 64 + tt) * 65 + cc] = bflo(v); L[(1 * 64 + tt) * 65 + cc] = bfhi(v); } }
.LBB0_811:
	v_mov_b32_e32 v22, 0
	s_andn2_b64 vcc, exec, s[6:7]
	v_mov_b32_e32 v25, 0
	v_mov_b32_e32 v26, 0
	v_mov_b32_e32 v27, 0
	v_mov_b32_e32 v29, 0
	v_mov_b32_e32 v30, 0
	v_mov_b32_e32 v31, 0
	v_mov_b32_e32 v32, 0
	s_cbranch_vccnz .LBB0_808
	s_add_i32 s9, s68, s11
	s_and_b32 s6, s9, 0x3c0
	s_add_i32 s10, s21, s12
	v_add_u32_e32 v26, s6, v11
	s_and_b32 s6, s10, 0xffffffc0
	s_ashr_i32 s7, s6, 31
	v_ashrrev_i32_e32 v27, 31, v26
	v_lshl_add_u64 v[30:31], s[6:7], 2, v[0:1]
	v_lshlrev_b64 v[26:27], 14, v[26:27]
	v_lshl_add_u64 v[32:33], v[30:31], 0, v[26:27]
	v_add_co_u32_e32 v26, vcc, 0x20000, v32
	global_load_dword v22, v[32:33], off
	s_nop 0
	v_addc_co_u32_e32 v27, vcc, 0, v33, vcc
	global_load_dword v25, v[26:27], off
	v_add_co_u32_e32 v26, vcc, s22, v32
	s_nop 1
	v_addc_co_u32_e32 v27, vcc, 0, v33, vcc
	v_add_co_u32_e32 v30, vcc, 0x60000, v32
	global_load_dword v26, v[26:27], off
	s_nop 0
	v_addc_co_u32_e32 v31, vcc, 0, v33, vcc
	global_load_dword v27, v[30:31], off
	v_add_co_u32_e32 v30, vcc, 0x80000, v32
	s_nop 1
	v_addc_co_u32_e32 v31, vcc, 0, v33, vcc
	global_load_dword v29, v[30:31], off
	v_add_co_u32_e32 v30, vcc, 0xa0000, v32
	s_nop 1
	v_addc_co_u32_e32 v31, vcc, 0, v33, vcc
	v_add_co_u32_e32 v34, vcc, 0xc0000, v32
	global_load_dword v30, v[30:31], off
	s_nop 0
	v_addc_co_u32_e32 v35, vcc, 0, v33, vcc
	v_add_co_u32_e32 v32, vcc, 0xe0000, v32
	s_nop 1
	v_addc_co_u32_e32 v33, vcc, 0, v33, vcc
	global_load_dword v32, v[32:33], off
	s_nop 0
	global_load_dword v31, v[34:35], off
	s_waitcnt vmcnt(15)
	v_lshlrev_b32_e32 v33, 16, v16
	s_waitcnt vmcnt(14)
	v_lshlrev_b32_e32 v34, 16, v17
	v_and_b32_e32 v16, 0xffff0000, v16
	ds_write2_b32 v13, v33, v34 offset1:8
	v_and_b32_e32 v17, 0xffff0000, v17
	v_add_u32_e32 v33, 0x4000, v13
	ds_write2_b32 v33, v16, v17 offset0:64 offset1:72
	s_waitcnt vmcnt(13)
	v_lshlrev_b32_e32 v16, 16, v18
	v_and_b32_e32 v17, 0xffff0000, v18
	s_waitcnt vmcnt(12)
	v_lshlrev_b32_e32 v18, 16, v19
	ds_write2_b32 v13, v16, v18 offset0:16 offset1:24
	v_and_b32_e32 v16, 0xffff0000, v19
	ds_write2_b32 v33, v17, v16 offset0:80 offset1:88
	s_waitcnt vmcnt(11)
	v_lshlrev_b32_e32 v16, 16, v21
	s_waitcnt vmcnt(10)
	v_lshlrev_b32_e32 v18, 16, v23
	v_and_b32_e32 v17, 0xffff0000, v21
	ds_write2_b32 v13, v16, v18 offset0:32 offset1:40
	v_and_b32_e32 v16, 0xffff0000, v23
	ds_write2_b32 v33, v17, v16 offset0:96 offset1:104
	s_waitcnt vmcnt(9)
	v_lshlrev_b32_e32 v16, 16, v24
	s_waitcnt vmcnt(8)
	v_lshlrev_b32_e32 v18, 16, v28
	v_and_b32_e32 v17, 0xffff0000, v24
	ds_write2_b32 v13, v16, v18 offset0:48 offset1:56
	v_and_b32_e32 v16, 0xffff0000, v28
	ds_write2_b32 v33, v17, v16 offset0:112 offset1:120
	s_branch .Lasm_tr_join
